# attention loop: 6 fewer scalar instructions per tile-step pair; row sums on two independent accumulators
# speedup vs baseline: 1.0133x; 1.0061x over previous
.Lattn_A_fast:
	s_lshl_b32 s80, s10, 14
	v_add_u32_e32 v179, s80, v219
	v_add_u32_e32 v126, v179, v149
	ds_read_b128 v[102:105], v126 offset:49152
	ds_read_b128 v[118:121], v126 offset:53248
	ds_read_b128 v[122:125], v126 offset:57344
	ds_read_b128 v[228:231], v126 offset:61440
	s_add_i32 s78, s34, -1
	s_add_i32 s63, s60, 0x80
	s_lshl_b32 s79, s62, 14
	s_cmp_gt_i32 s78, s48
	s_cselect_b32 s4, 0, 1
	s_waitcnt lgkmcnt(2)
	v_mfma_f32_32x32x16_bf16 v[50:65], v[102:105], v[98:101], v[50:65]
	v_exp_f32_e32 v66, v66
	v_exp_f32_e32 v249, v82
	v_add_u32_e32 v181, v179, v208
	ds_read_b128 v[102:105], v181 offset:49152
	v_mfma_f32_32x32x16_bf16 v[34:49], v[118:121], v[98:101], v[34:49]
	v_add_f32_e32 v254, 0, v66
	v_add_f32_e32 v255, 0, v249
	v_exp_f32_e32 v67, v67
	v_exp_f32_e32 v250, v83
	ds_read_b128 v[232:235], v181 offset:53248
	s_waitcnt lgkmcnt(2)
	v_mfma_f32_32x32x16_bf16 v[18:33], v[122:125], v[98:101], v[18:33]
	v_add_f32_e32 v254, v67, v254
	v_add_f32_e32 v255, v250, v255
	v_exp_f32_e32 v68, v68
	v_exp_f32_e32 v195, v84
	ds_read_b128 v[126:129], v181 offset:57344
	v_mfma_f32_32x32x16_bf16 v[2:17], v[228:231], v[98:101], v[2:17]
	v_add_f32_e32 v254, v68, v254
	v_add_f32_e32 v255, v195, v255
	v_exp_f32_e32 v69, v69
	v_exp_f32_e32 v251, v85
	ds_read_b128 v[118:121], v181 offset:61440
	s_waitcnt lgkmcnt(2)
	v_mfma_f32_32x32x16_bf16 v[50:65], v[102:105], v[106:109], v[50:65]
	v_add_f32_e32 v254, v69, v254
	v_add_f32_e32 v255, v251, v255
	v_exp_f32_e32 v70, v70
	v_exp_f32_e32 v252, v86
	v_add_u32_e32 v181, v179, v209
	ds_read_b128 v[122:125], v181 offset:49152
	v_mfma_f32_32x32x16_bf16 v[34:49], v[232:235], v[106:109], v[34:49]
	s_cbranch_scc1 .LBB0_458
	s_add_i32 s78, s34, -3
	s_add_i32 s81, s60, 0x100
	s_cmp_lt_i32 s78, s39
	s_cselect_b32 s82, s63, s81
	s_ashr_i32 s83, s82, 31
	s_lshl_b64 s[82:83], s[82:83], 12
	s_add_i32 s78, s79, 0xffffc000
	s_cmp_lg_u32 s62, 0
	s_cselect_b32 s78, s78, 0x8000
	v_lshl_add_u64 v[98:99], v[202:203], 0, s[82:83]
	s_add_i32 s78, s7, s78
	s_mov_b32 m0, s78
	v_lshl_add_u64 v[100:101], v[98:99], 0, s[30:31]
	global_load_lds_dwordx4 v[100:101], off
	s_add_i32 m0, s78, 0x2000
	v_lshl_add_u64 v[98:99], v[98:99], 0, s[36:37]
	global_load_lds_dwordx4 v[98:99], off
.LBB0_458:
	s_add_i32 s78, s34, -4
	s_cmp_gt_i32 s78, s39
	s_cselect_b64 vcc, -1, 0
	s_cselect_b32 s82, s63, s60
	v_cndmask_b32_e64 v200, v201, -v201, vcc
	s_ashr_i32 s83, s82, 31
	s_lshl_b64 s[84:85], s[82:83], 1
	s_addk_i32 s80, 0xc000
	s_cmp_lg_u32 s10, 0
	s_cselect_b32 s80, s80, 0x8000
	s_add_i32 s80, s14, s80
	v_lshl_add_u64 v[98:99], v[204:205], 0, s[84:85]
	s_add_i32 m0, s80, 0xc000
	v_lshl_add_u64 v[100:101], v[206:207], 0, s[84:85]
	global_load_lds_dwordx4 v[98:99], off
	s_add_i32 m0, s80, 0xc400
	v_cvt_f32_i32_e32 v98, s82
	global_load_lds_dwordx4 v[100:101], off
	v_add_u32_e32 v183, s79, v218
	v_add_f32_e32 v98, v155, v98
	v_fma_f32 v224, v200, v98, -v199
	v_fma_f32 v98, 0, v200, v224
	v_add_f32_e32 v99, v200, v224
	v_fma_f32 v100, v200, s64, v224
	v_fma_f32 v101, v200, s65, v224
	v_fma_f32 v102, v200, s66, v224
	v_fma_f32 v103, v200, s67, v224
	v_mul_f32_e32 v240, 0x42000000, v200
	ds_read_b128 v[228:231], v181 offset:53248
	s_waitcnt lgkmcnt(2)
	v_mfma_f32_32x32x16_bf16 v[18:33], v[126:129], v[106:109], v[18:33]
	v_add_f32_e32 v254, v70, v254
	v_add_f32_e32 v255, v252, v255
	v_exp_f32_e32 v71, v71
	v_fma_f32 v104, v200, s68, v224
	v_fma_f32 v105, v200, s69, v224
	ds_read_b128 v[126:129], v181 offset:57344
	v_mfma_f32_32x32x16_bf16 v[2:17], v[118:121], v[106:109], v[2:17]
	s_setprio 0
	v_add_f32_e32 v254, v71, v254
	v_exp_f32_e32 v253, v87
	v_exp_f32_e32 v82, v72
	ds_read_b128 v[118:121], v181 offset:61440
	s_waitcnt lgkmcnt(2)
	v_mfma_f32_32x32x16_bf16 v[50:65], v[122:125], v[110:113], v[50:65]
	v_add_f32_e32 v255, v253, v255
	v_add_f32_e32 v254, v82, v254
	v_exp_f32_e32 v72, v88
	v_fma_f32 v106, v200, s70, v224
	v_fma_f32 v107, v200, s71, v224
	v_add_u32_e32 v179, v179, v226
	ds_read_b128 v[122:125], v179 offset:49152
	v_mfma_f32_32x32x16_bf16 v[34:49], v[228:231], v[110:113], v[34:49]
	v_add_f32_e32 v255, v72, v255
	v_exp_f32_e32 v83, v73
	v_exp_f32_e32 v73, v89
	ds_read_b128 v[228:231], v179 offset:53248
	s_waitcnt lgkmcnt(2)
	v_mfma_f32_32x32x16_bf16 v[18:33], v[126:129], v[110:113], v[18:33]
	v_add_f32_e32 v254, v83, v254
	v_add_f32_e32 v255, v73, v255
	v_exp_f32_e32 v74, v74
	v_fma_f32 v108, v200, s72, v224
	v_fma_f32 v109, v200, s73, v224
	ds_read_b128 v[126:129], v179 offset:57344
	v_mfma_f32_32x32x16_bf16 v[2:17], v[118:121], v[110:113], v[2:17]
	v_add_f32_e32 v254, v74, v254
	v_exp_f32_e32 v90, v90
	v_exp_f32_e32 v75, v75
	ds_read_b128 v[118:121], v179 offset:61440
	s_waitcnt lgkmcnt(2)
	v_mfma_f32_32x32x16_bf16 v[50:65], v[122:125], v[114:117], v[50:65]
	v_add_f32_e32 v255, v90, v255
	v_add_f32_e32 v254, v75, v254
	v_exp_f32_e32 v91, v91
	v_fma_f32 v110, v200, s74, v224
	v_fma_f32 v111, v200, s75, v224
	v_add_u32_e32 v112, v183, v149
	ds_read_b128 v[232:235], v112
	v_mfma_f32_32x32x16_bf16 v[34:49], v[228:231], v[114:117], v[34:49]
	v_add_f32_e32 v255, v91, v255
	v_exp_f32_e32 v76, v76
	v_exp_f32_e32 v92, v92
	ds_read_b128 v[228:231], v112 offset:4096
	s_waitcnt lgkmcnt(2)
	v_mfma_f32_32x32x16_bf16 v[18:33], v[126:129], v[114:117], v[18:33]
	v_add_f32_e32 v254, v76, v254
	v_add_f32_e32 v255, v92, v255
	v_exp_f32_e32 v77, v77
	v_fma_f32 v112, v200, s76, v224
	v_fma_f32 v113, v200, s77, v224
	v_add_u32_e32 v179, v183, v208
	ds_read_b128 v[236:239], v179
	v_mfma_f32_32x32x16_bf16 v[2:17], v[118:121], v[114:117], v[2:17]
	v_add_f32_e64 v114, v240, v98
	v_add_f32_e64 v115, v240, v99
	v_add_f32_e64 v128, v240, v112
	v_add_f32_e64 v129, v240, v113
	v_add_f32_e64 v126, v240, v110
	v_add_f32_e64 v127, v240, v111
	v_add_f32_e32 v124, v240, v108
	v_add_f32_e32 v125, v240, v109
	v_add_f32_e32 v122, v240, v106
	v_add_f32_e32 v123, v240, v107
	v_add_f32_e32 v120, v240, v104
	v_add_f32_e32 v121, v240, v105
	v_add_f32_e32 v118, v240, v102
	v_add_f32_e32 v119, v240, v103
	v_add_f32_e32 v116, v240, v100
	v_add_f32_e32 v117, v240, v101
	ds_read_b128 v[240:243], v179 offset:4096
	s_waitcnt lgkmcnt(2)
	v_mfma_f32_32x32x16_bf16 v[98:113], v[232:235], v[130:133], v[98:113]
	v_add_f32_e32 v254, v77, v254
	v_exp_f32_e32 v93, v93
	v_exp_f32_e32 v78, v78
	v_add_u32_e32 v179, v183, v209
	ds_read_b128 v[232:235], v179
	v_mfma_f32_32x32x16_bf16 v[114:129], v[228:231], v[130:133], v[114:129]
	v_add_f32_e32 v255, v93, v255
	v_add_f32_e32 v254, v78, v254
	v_exp_f32_e32 v94, v94
	v_exp_f32_e32 v79, v79
	ds_read_b128 v[228:231], v179 offset:4096
	s_waitcnt lgkmcnt(2)
	v_mfma_f32_32x32x16_bf16 v[98:113], v[236:239], v[134:137], v[98:113]
	v_add_f32_e32 v255, v94, v255
	v_add_f32_e32 v254, v79, v254
	v_exp_f32_e32 v95, v95
	v_exp_f32_e32 v80, v80
	v_add_u32_e32 v179, v183, v226
	ds_read_b128 v[236:239], v179
	v_mfma_f32_32x32x16_bf16 v[114:129], v[240:243], v[134:137], v[114:129]
	v_add_f32_e32 v255, v95, v255
	v_add_f32_e32 v254, v80, v254
	v_exp_f32_e32 v96, v96
	v_exp_f32_e32 v81, v81
	ds_read_b128 v[240:243], v179 offset:4096
	s_waitcnt lgkmcnt(2)
	v_mfma_f32_32x32x16_bf16 v[98:113], v[232:235], v[138:141], v[98:113]
	v_add_f32_e32 v255, v96, v255
	v_add_f32_e32 v254, v81, v254
	v_exp_f32_e32 v97, v97
	v_mfma_f32_32x32x16_bf16 v[114:129], v[228:231], v[138:141], v[114:129]
	v_add_f32_e32 v255, v97, v255
	v_add_f32_e32 v254, v255, v254
	s_waitcnt lgkmcnt(0)
	v_mfma_f32_32x32x16_bf16 v[98:113], v[236:239], v[142:145], v[98:113]
	v_mfma_f32_32x32x16_bf16 v[114:129], v[240:243], v[142:145], v[114:129]
	s_cmp_lg_u32 s4, 0
	s_cbranch_scc0 .LBB0_471
	s_waitcnt vmcnt(4) lgkmcnt(0)
	s_barrier
	s_cmp_eq_u32 s100, 0
	s_cbranch_scc1 .Lattn_fair_a
	s_setprio 1

.LBB0_464:
	s_add_i32 s4, s62, 1
	s_cmp_lg_u32 s62, 2
	s_cselect_b32 s4, s4, 0
	s_add_i32 s5, s10, 1
	s_cmp_lg_u32 s10, 2
	s_cselect_b32 s5, s5, 0
	s_lshl_b32 s62, s5, 14
	v_add_u32_e32 v198, s62, v219
	v_cvt_pk_bf16_f32 v66, v66, v67
	v_cvt_pk_bf16_f32 v67, v68, v69
	v_cvt_pk_bf16_f32 v68, v70, v71
	v_add_u32_e32 v70, v198, v149
	v_cvt_pk_bf16_f32 v69, v82, v83
	v_cvt_pk_bf16_f32 v74, v74, v75
	v_cvt_pk_bf16_f32 v75, v76, v77
	v_cvt_pk_bf16_f32 v76, v78, v79
	v_cvt_pk_bf16_f32 v77, v80, v81
	ds_read_b128 v[78:81], v70 offset:49152
	ds_read_b128 v[82:85], v70 offset:53248
	ds_read_b128 v[86:89], v70 offset:57344
	ds_read_b128 v[228:231], v70 offset:61440
	s_lshl_b32 s10, s4, 14
	s_cmp_gt_i32 s34, s48
	s_waitcnt lgkmcnt(2)
	v_mfma_f32_32x32x16_bf16 v[50:65], v[78:81], v[66:69], v[50:65]
	v_add_u32_e32 v70, v198, v208
	ds_read_b128 v[78:81], v70 offset:49152
	v_mfma_f32_32x32x16_bf16 v[34:49], v[82:85], v[66:69], v[34:49]
	ds_read_b128 v[232:235], v70 offset:53248
	s_waitcnt lgkmcnt(2)
	v_mfma_f32_32x32x16_bf16 v[18:33], v[86:89], v[66:69], v[18:33]
	ds_read_b128 v[86:89], v70 offset:57344
	v_mfma_f32_32x32x16_bf16 v[2:17], v[228:231], v[66:69], v[2:17]
	ds_read_b128 v[82:85], v70 offset:61440
	s_waitcnt lgkmcnt(2)
	v_mfma_f32_32x32x16_bf16 v[50:65], v[78:81], v[74:77], v[50:65]
	v_add_u32_e32 v227, v198, v209
	ds_read_b128 v[78:81], v227 offset:49152
	v_mfma_f32_32x32x16_bf16 v[34:49], v[232:235], v[74:77], v[34:49]
	s_cbranch_scc1 .LBB0_466
	s_cmp_lt_i32 s61, s39
	s_movk_i32 s79, 0xc0
	s_cselect_b32 s79, s79, 0x140
	s_add_i32 s80, s60, s79
	s_ashr_i32 s81, s80, 31
	s_lshl_b64 s[80:81], s[80:81], 12
	s_add_i32 s60, s10, 0xffffc000
	s_cmp_lg_u32 s4, 0
	s_cselect_b32 s60, s60, 0x8000
	v_lshl_add_u64 v[66:67], v[202:203], 0, s[80:81]
	s_add_i32 s60, s7, s60
	s_mov_b32 m0, s60
	v_lshl_add_u64 v[68:69], v[66:67], 0, s[30:31]
	global_load_lds_dwordx4 v[68:69], off
	s_add_i32 m0, s60, 0x2000
	v_lshl_add_u64 v[66:67], v[66:67], 0, s[36:37]
	global_load_lds_dwordx4 v[66:67], off
.LBB0_466:
	s_cmp_lt_i32 s78, s39
	s_cselect_b64 vcc, -1, 0
	s_cselect_b32 s60, s78, s61
	v_cndmask_b32_e64 v228, -v201, v201, vcc
	s_add_i32 s60, s60, s33
	s_lshl_b32 s78, s60, 6
	s_ashr_i32 s79, s78, 31
	s_lshl_b64 s[80:81], s[78:79], 1
	s_addk_i32 s62, 0xc000
	s_cmp_lg_u32 s5, 0
	s_cselect_b32 s60, s62, 0x8000
	s_add_i32 s60, s14, s60
	v_lshl_add_u64 v[66:67], v[204:205], 0, s[80:81]
	s_add_i32 m0, s60, 0xc000
	v_lshl_add_u64 v[68:69], v[206:207], 0, s[80:81]
	global_load_lds_dwordx4 v[66:67], off
	s_add_i32 m0, s60, 0xc400
	v_cvt_f32_i32_e32 v66, s78
	global_load_lds_dwordx4 v[68:69], off
	v_exp_f32_e32 v231, v98
	v_add_f32_e32 v66, v155, v66
	v_fma_f32 v230, v228, v66, -v199
	v_add_u32_e32 v229, s10, v218
	v_exp_f32_e32 v233, v114
	v_fma_f32 v66, 0, v228, v230
	v_exp_f32_e32 v234, v99
	v_exp_f32_e32 v235, v115
	v_add_f32_e32 v67, v228, v230
	v_exp_f32_e32 v236, v100
	v_exp_f32_e32 v237, v116
	v_exp_f32_e32 v238, v101
	v_exp_f32_e32 v239, v117
	v_fma_f32 v68, v228, s64, v230
	v_fma_f32 v69, v228, s65, v230
	v_fma_f32 v70, v228, s66, v230
	v_fma_f32 v71, v228, s67, v230
	v_cvt_pk_bf16_f32 v98, v249, v250
	v_cvt_pk_bf16_f32 v99, v195, v251
	v_cvt_pk_bf16_f32 v100, v252, v253
	v_cvt_pk_bf16_f32 v101, v72, v73
	v_cvt_pk_bf16_f32 v114, v90, v91
	v_cvt_pk_bf16_f32 v115, v92, v93
	v_cvt_pk_bf16_f32 v116, v94, v95
	v_cvt_pk_bf16_f32 v117, v96, v97
	v_mul_f32_e32 v232, 0x42000000, v228
	v_exp_f32_e32 v240, v102
	v_exp_f32_e32 v241, v118
	v_exp_f32_e32 v242, v103
	v_exp_f32_e32 v243, v119
	ds_read_b128 v[90:93], v227 offset:53248
	s_waitcnt lgkmcnt(2)
	v_mfma_f32_32x32x16_bf16 v[18:33], v[86:89], v[74:77], v[18:33]
	v_add_f32_e32 v254, 0, v231
	v_add_f32_e32 v255, 0, v233
	v_fma_f32 v72, v228, s68, v230
	v_fma_f32 v73, v228, s69, v230
	v_exp_f32_e32 v181, v104
	v_exp_f32_e32 v183, v120
	ds_read_b128 v[86:89], v227 offset:57344
	v_mfma_f32_32x32x16_bf16 v[2:17], v[82:85], v[74:77], v[2:17]
	s_setprio 0
	v_add_f32_e32 v254, v234, v254
	v_add_f32_e32 v255, v235, v255
	v_exp_f32_e32 v195, v105
	v_exp_f32_e32 v200, v121
	ds_read_b128 v[82:85], v227 offset:61440
	s_waitcnt lgkmcnt(2)
	v_mfma_f32_32x32x16_bf16 v[50:65], v[78:81], v[98:101], v[50:65]
	v_add_f32_e32 v254, v236, v254
	v_add_f32_e32 v255, v237, v255
	v_fma_f32 v74, v228, s70, v230
	v_fma_f32 v75, v228, s71, v230
	v_exp_f32_e32 v224, v106
	v_exp_f32_e32 v122, v122
	v_add_u32_e32 v78, v198, v226
	ds_read_b128 v[94:97], v78 offset:49152
	v_mfma_f32_32x32x16_bf16 v[34:49], v[90:93], v[98:101], v[34:49]
	v_add_f32_e32 v254, v238, v254
	v_add_f32_e32 v255, v239, v255
	v_exp_f32_e32 v225, v107
	v_exp_f32_e32 v123, v123
	ds_read_b128 v[90:93], v78 offset:53248
	s_waitcnt lgkmcnt(2)
	v_mfma_f32_32x32x16_bf16 v[18:33], v[86:89], v[98:101], v[18:33]
	v_add_f32_e32 v254, v240, v254
	v_add_f32_e32 v255, v241, v255
	v_fma_f32 v76, v228, s72, v230
	v_fma_f32 v77, v228, s73, v230
	v_exp_f32_e32 v227, v108
	v_exp_f32_e32 v124, v124
	ds_read_b128 v[86:89], v78 offset:57344
	v_mfma_f32_32x32x16_bf16 v[2:17], v[82:85], v[98:101], v[2:17]
	v_add_f32_e32 v254, v242, v254
	v_add_f32_e32 v255, v243, v255
	v_exp_f32_e32 v244, v109
	v_exp_f32_e32 v125, v125
	ds_read_b128 v[98:101], v78 offset:61440
	s_waitcnt lgkmcnt(2)
	v_mfma_f32_32x32x16_bf16 v[50:65], v[94:97], v[114:117], v[50:65]
	v_add_f32_e32 v254, v181, v254
	v_add_f32_e32 v255, v183, v255
	v_fma_f32 v78, v228, s74, v230
	v_fma_f32 v79, v228, s75, v230
	v_exp_f32_e32 v245, v110
	v_exp_f32_e32 v126, v126
	v_add_u32_e32 v80, v229, v149
	ds_read_b128 v[102:105], v80
	v_mfma_f32_32x32x16_bf16 v[34:49], v[90:93], v[114:117], v[34:49]
	v_add_f32_e32 v254, v195, v254
	v_add_f32_e32 v255, v200, v255
	v_exp_f32_e32 v246, v111
	v_exp_f32_e32 v127, v127
	ds_read_b128 v[106:109], v80 offset:4096
	s_waitcnt lgkmcnt(2)
	v_mfma_f32_32x32x16_bf16 v[18:33], v[86:89], v[114:117], v[18:33]
	v_add_f32_e32 v254, v224, v254
	v_add_f32_e32 v255, v122, v255
	v_fma_f32 v80, v228, s76, v230
	v_fma_f32 v81, v228, s77, v230
	v_exp_f32_e32 v247, v112
	v_exp_f32_e32 v128, v128
	v_add_u32_e32 v110, v229, v208
	ds_read_b128 v[118:121], v110
	v_mfma_f32_32x32x16_bf16 v[2:17], v[98:101], v[114:117], v[2:17]
	v_add_f32_e32 v254, v225, v254
	v_add_f32_e32 v255, v123, v255
	v_add_f32_e64 v82, v232, v66
	v_add_f32_e64 v83, v232, v67
	v_add_f32_e64 v96, v232, v80
	v_add_f32_e64 v97, v232, v81
	v_add_f32_e64 v94, v232, v78
	v_add_f32_e64 v95, v232, v79
	v_add_f32_e32 v92, v232, v76
	v_add_f32_e32 v93, v232, v77
	v_add_f32_e32 v90, v232, v74
	v_add_f32_e32 v91, v232, v75
	v_add_f32_e32 v88, v232, v72
	v_add_f32_e32 v89, v232, v73
	v_add_f32_e32 v86, v232, v70
	v_add_f32_e32 v87, v232, v71
	v_add_f32_e32 v84, v232, v68
	v_add_f32_e32 v85, v232, v69
	v_exp_f32_e32 v228, v113
	v_exp_f32_e32 v129, v129
	ds_read_b128 v[98:101], v110 offset:4096
	s_waitcnt lgkmcnt(2)
	v_mfma_f32_32x32x16_bf16 v[66:81], v[102:105], v[130:133], v[66:81]
	v_add_f32_e32 v254, v227, v254
	v_add_f32_e32 v255, v124, v255
	v_add_f32_e32 v254, v244, v254
	v_add_u32_e32 v110, v229, v209
	ds_read_b128 v[102:105], v110
	v_mfma_f32_32x32x16_bf16 v[82:97], v[106:109], v[130:133], v[82:97]
	v_add_f32_e32 v255, v125, v255
	v_add_f32_e32 v254, v245, v254
	v_add_f32_e32 v255, v126, v255
	ds_read_b128 v[106:109], v110 offset:4096
	s_waitcnt lgkmcnt(2)
	v_mfma_f32_32x32x16_bf16 v[66:81], v[118:121], v[134:137], v[66:81]
	v_add_f32_e32 v254, v246, v254
	v_add_f32_e32 v255, v127, v255
	v_add_f32_e32 v254, v247, v254
	v_add_u32_e32 v114, v229, v226
	ds_read_b128 v[110:113], v114
	v_mfma_f32_32x32x16_bf16 v[82:97], v[98:101], v[134:137], v[82:97]
	v_add_f32_e32 v255, v128, v255
	v_add_f32_e32 v254, v228, v254
	v_add_f32_e32 v255, v129, v255
	v_add_f32_e32 v254, v255, v254
	ds_read_b128 v[98:101], v114 offset:4096
	s_waitcnt lgkmcnt(2)
	v_mfma_f32_32x32x16_bf16 v[66:81], v[102:105], v[138:141], v[66:81]
	v_cvt_pk_bf16_f32 v114, v122, v123
	v_cvt_pk_bf16_f32 v115, v124, v125
	v_cvt_pk_bf16_f32 v116, v126, v127
	v_cvt_pk_bf16_f32 v117, v128, v129
	v_mfma_f32_32x32x16_bf16 v[82:97], v[106:109], v[138:141], v[82:97]
	v_cvt_pk_bf16_f32 v106, v224, v225
	v_cvt_pk_bf16_f32 v107, v227, v244
	v_cvt_pk_bf16_f32 v108, v245, v246
	v_cvt_pk_bf16_f32 v109, v247, v228
	s_waitcnt lgkmcnt(0)
	v_mfma_f32_32x32x16_bf16 v[66:81], v[110:113], v[142:145], v[66:81]
	v_cvt_pk_bf16_f32 v110, v233, v235
	v_cvt_pk_bf16_f32 v111, v237, v239
	v_cvt_pk_bf16_f32 v112, v241, v243
	v_cvt_pk_bf16_f32 v113, v183, v200
	v_mfma_f32_32x32x16_bf16 v[82:97], v[98:101], v[142:145], v[82:97]
	s_add_i32 s10, s4, 1
	s_cmp_lg_u32 s4, 2
	s_cselect_b32 s62, s10, 0
	s_add_i32 s4, s5, 1
	s_cmp_lg_u32 s5, 2
	s_cselect_b32 s10, s4, 0
	s_add_i32 s34, s34, 2
	v_add_f32_e32 v198, v179, v254
	v_cvt_pk_bf16_f32 v98, v231, v234
	v_cvt_pk_bf16_f32 v99, v236, v238
	v_cvt_pk_bf16_f32 v100, v240, v242
	v_cvt_pk_bf16_f32 v101, v181, v195
	s_cmp_ge_i32 s61, s48
	s_cbranch_scc1 .LBB0_473
	s_mov_b32 s60, s63
	s_add_i32 s61, s34, -2
	s_cmp_gt_i32 s61, s48
	s_cbranch_scc1 .LBB0_469
